# D-phase epilogue (conv3+silu*up) rewritten by hand: select-before-rotate with DPP-fused FMAs, staged 8-wide interleave, no dead zero-inits or nops; row-sum loads waited separately from conv-weight loa
# speedup vs baseline: 1.0337x; 1.0139x over previous
.LBB0_120:
	v_readlane_b32 s30, v254, 52
	v_readlane_b32 s40, v252, 4
	s_mul_i32 s25, s30, 0x8400
	v_readlane_b32 s44, v252, 8
	s_mul_hi_i32 s1, s30, 0x8400
	v_readlane_b32 s45, v252, 9
	s_add_u32 s68, s44, s25
	v_readlane_b32 s46, v252, 10
	s_addc_u32 s69, s45, s1
	s_mul_i32 s25, s30, 0x2c00
	v_readlane_b32 s47, v252, 11
	s_mul_hi_i32 s1, s30, 0x2c00
	s_add_u32 s70, s46, s25
	s_addc_u32 s71, s47, s1
	s_mul_i32 s25, s38, 0x1c00000
	v_readlane_b32 s20, v252, 32
	s_mul_hi_i32 s1, s38, 0x1c00000
	s_add_u32 s27, s20, s25
	v_readlane_b32 s20, v252, 33
	v_readlane_b32 s31, v254, 53
	s_addc_u32 s30, s20, s1
	s_mul_i32 s33, s38, 0xfea00000
	s_mul_hi_i32 s31, s38, 0xfea00000
	s_add_u32 s94, s27, s33
	s_addc_u32 s95, s30, s31
	s_add_u32 s25, s54, s25
	s_addc_u32 s1, s55, s1
	s_mul_i32 s30, s38, 0xffea0000
	s_mul_hi_i32 s27, s38, 0xffea0000
	s_add_u32 s25, s25, s30
	s_addc_u32 s1, s1, s27
	s_add_u32 s52, s25, 0x5600000
	s_addc_u32 s53, s1, 0
	s_add_u32 s50, s25, 0x5780000
	s_addc_u32 s51, s1, 0
	v_lshrrev_b32_e32 v15, 1, v14
	s_add_u32 s92, s25, 0x5900000
	v_and_b32_e32 v15, 24, v15
	s_addc_u32 s93, s1, 0
	v_and_b32_e32 v216, 15, v14
	s_lshl_b32 s1, s10, 6
	v_lshlrev_b32_e32 v16, 1, v15
	v_lshlrev_b32_e32 v14, 2, v14
	v_writelane_b32 v254, s1, 61
	v_lshl_or_b32 v16, v216, 6, v16
	s_lshl_b32 s1, s10, 13
	v_and_b32_e32 v14, 32, v14
	v_bitop3_b32 v17, v16, s1, v14 bitop3:0xde
	s_lshl_b32 s1, s11, 5
	s_and_b32 s1, s1, 0x60
	s_add_i32 m0, s75, 0x18000
	v_lshl_add_u64 v[6:7], v[6:7], 0, s[18:19]
	s_lshl_b32 s10, s1, 7
	s_waitcnt vmcnt(4)
	s_barrier
	global_load_lds_dwordx4 v[6:7], off
	v_lshl_add_u64 v[4:5], v[4:5], 0, s[18:19]
	s_add_i32 m0, s75, 0x1a000
	s_add_i32 s31, s75, 0x8000
	s_add_i32 s34, s75, 0xa000
	v_bitop3_b32 v217, v16, s10, v14 bitop3:0xde
	global_load_lds_dwordx4 v[4:5], off
	v_lshl_add_u64 v[2:3], v[2:3], 0, s[18:19]
	s_mov_b32 m0, s31
	s_add_u32 s10, s82, 0x40080
	global_load_lds_dwordx4 v[2:3], off
	v_lshl_add_u64 v[0:1], v[0:1], 0, s[18:19]
	s_mov_b32 m0, s34
	s_addc_u32 s11, s83, 0
	global_load_lds_dwordx4 v[0:1], off
	s_add_i32 m0, s75, 0x1c000
	v_lshl_add_u64 v[0:1], s[10:11], 0, v[144:145]
	global_load_lds_dwordx4 v[0:1], off
	v_lshl_add_u64 v[0:1], s[10:11], 0, v[162:163]
	s_add_i32 m0, s75, 0x1e000
	s_ashr_i32 s30, s8, 31
	global_load_lds_dwordx4 v[0:1], off
	v_lshlrev_b32_e32 v0, 14, v8
	v_and_b32_e32 v0, 0xffff8000, v0
	v_lshl_add_u32 v0, v9, 11, v0
	v_and_b32_e32 v1, 1, v8
	v_lshl_or_b32 v0, v1, 6, v0
	v_lshl_add_u32 v164, v10, 1, v0
	v_lshlrev_b32_e32 v0, 14, v11
	s_add_u32 s60, s68, 0x2c00
	v_and_b32_e32 v0, 0xffff8000, v0
	s_waitcnt vmcnt(6)
	s_addc_u32 s61, s69, 0
	v_lshl_add_u32 v0, v12, 11, v0
	v_and_b32_e32 v1, 1, v11
	v_readlane_b32 s41, v252, 5
	v_readlane_b32 s42, v252, 6
	v_readlane_b32 s43, v252, 7
	s_add_u32 s64, s68, 0x5800
	v_lshl_or_b32 v0, v1, 6, v0
	v_readlane_b32 s48, v252, 38
	s_mov_b32 s35, 0
	v_cmp_eq_u32_e64 s[38:39], 0, v216
	v_cmp_lt_u32_e64 s[40:41], 1, v216
	v_cmp_gt_u32_e64 s[42:43], 2, v216
	v_cmp_lt_u32_e64 s[44:45], 13, v216
	v_add_u32_e32 v218, -14, v216
	s_addc_u32 s65, s69, 0
	v_or_b32_e32 v219, s1, v15
	v_mov_b32_e32 v165, v145
	v_lshl_add_u32 v166, v13, 1, v0
	v_mov_b32_e32 v167, v145
	v_add_u32_e32 v220, 0, v17
	v_readlane_b32 s49, v252, 39
	s_barrier
	s_branch .LBB0_122
.LBB0_122:
	s_add_i32 s35, s35, 1
	v_readlane_b32 s1, v252, 40
	s_mul_i32 s1, s35, s1
	s_mul_hi_u32 s10, s35, s4
	s_add_i32 s10, s10, s1
	s_mul_i32 s1, s35, s4
	s_add_u32 s72, s1, s8
	s_addc_u32 s73, s10, s30
	v_mov_b64_e32 v[0:1], 0xaff
	v_cmp_gt_i64_e64 s[46:47], s[72:73], v[0:1]
	s_and_b64 vcc, exec, s[46:47]
	s_cbranch_vccnz .LBB0_124
	s_ashr_i32 s1, s72, 31
	s_lshr_b32 s1, s1, 29
	s_add_i32 s1, s72, s1
	s_ashr_i32 s10, s1, 3
	s_and_b32 s1, s1, -8
	s_sub_i32 s1, s72, s1
	s_cmp_lt_i32 s1, 0
	s_movk_i32 s11, 0x161
	s_cselect_b32 s11, s11, 0x160
	s_mul_i32 s1, s11, s1
	s_add_i32 s1, s1, s10
	s_mul_hi_i32 s10, s1, 0x2e8ba2e9
	s_lshr_b32 s11, s10, 31
	s_ashr_i32 s10, s10, 5
	s_add_i32 s10, s10, s11
	s_lshl_b32 s11, s10, 3
	s_sub_i32 s25, 0x80, s11
	s_min_i32 s25, s25, 8
	s_abs_i32 s27, s25
	v_cvt_f32_u32_e32 v0, s27
	s_sub_i32 s36, 0, s27
	s_mulk_i32 s10, 0xb0
	s_sub_i32 s1, s1, s10
	v_rcp_iflag_f32_e32 v0, v0
	s_abs_i32 s10, s1
	s_xor_b32 s33, s1, s25
	s_ashr_i32 s33, s33, 31
	v_mul_f32_e32 v0, 0x4f7ffffe, v0
	v_cvt_u32_f32_e32 v0, v0
	s_nop 0
	v_readfirstlane_b32 s37, v0
	s_mul_i32 s36, s36, s37
	s_mul_hi_u32 s36, s37, s36
	s_add_i32 s37, s37, s36
	s_mul_hi_u32 s36, s10, s37
	s_mul_i32 s37, s36, s27
	s_sub_i32 s10, s10, s37
	s_add_i32 s56, s36, 1
	s_sub_i32 s37, s10, s27
	s_cmp_ge_u32 s10, s27
	s_cselect_b32 s36, s56, s36
	s_cselect_b32 s10, s37, s10
	s_add_i32 s37, s36, 1
	s_cmp_ge_u32 s10, s27
	s_cselect_b32 s10, s37, s36
	s_xor_b32 s10, s10, s33
	s_sub_i32 s76, s10, s33
	s_mul_i32 s10, s76, s25
	s_sub_i32 s1, s1, s10
	s_add_i32 s78, s1, s11

.LBB0_125:
	s_add_u32 s27, s86, 0xfffc0080
	s_addc_u32 s56, s87, -1
	s_add_i32 s57, 0, 0x10000
	v_add_u32_e32 v76, s57, v217
	ds_read_b128 v[64:67], v76
	ds_read_b128 v[68:71], v76 offset:1024
	ds_read_b128 v[72:75], v76 offset:2048
	ds_read_b128 v[76:79], v76 offset:3072
	s_cmp_eq_u32 s37, 12
	s_cselect_b32 vcc_hi, s1, s56
	s_cselect_b32 vcc_lo, s10, s27
	s_cselect_b32 s83, s11, s36
	s_cselect_b32 s82, s25, s33
	v_lshl_add_u64 v[168:169], s[86:87], 0, v[164:165]
	s_add_i32 m0, s75, 0xc000
	ds_read_b128 v[80:83], v220
	ds_read_b128 v[84:87], v220 offset:1024
	ds_read_b128 v[88:91], v220 offset:2048
	ds_read_b128 v[92:95], v220 offset:3072
	ds_read_b128 v[188:191], v220 offset:4096
	ds_read_b128 v[192:195], v220 offset:5120
	ds_read_b128 v[196:199], v220 offset:6144
	ds_read_b128 v[200:203], v220 offset:7168
	global_load_lds_dwordx4 v[168:169], off
	v_lshl_add_u64 v[168:169], s[86:87], 0, v[166:167]
	s_add_i32 m0, s75, 0xe000
	s_nop 0
	global_load_lds_dwordx4 v[168:169], off
	s_waitcnt lgkmcnt(8)
	s_barrier
	s_waitcnt lgkmcnt(0)
	s_setprio 1
	s_waitcnt lgkmcnt(0)
	v_mfma_f32_16x16x32_bf16 v[146:149], v[64:67], v[80:83], v[146:149]
	v_mfma_f32_16x16x32_bf16 v[116:119], v[72:75], v[80:83], v[116:119]
	v_mfma_f32_16x16x32_bf16 v[158:161], v[64:67], v[88:91], v[158:161]
	v_mfma_f32_16x16x32_bf16 v[124:127], v[72:75], v[88:91], v[124:127]
	v_mfma_f32_16x16x32_bf16 v[154:157], v[64:67], v[188:191], v[154:157]
	v_mfma_f32_16x16x32_bf16 v[112:115], v[72:75], v[188:191], v[112:115]
	v_mfma_f32_16x16x32_bf16 v[150:153], v[64:67], v[196:199], v[150:153]
	v_mfma_f32_16x16x32_bf16 v[120:123], v[72:75], v[196:199], v[120:123]
	v_mfma_f32_16x16x32_bf16 v[146:149], v[68:71], v[84:87], v[146:149]
	v_mfma_f32_16x16x32_bf16 v[116:119], v[76:79], v[84:87], v[116:119]
	v_mfma_f32_16x16x32_bf16 v[158:161], v[68:71], v[92:95], v[158:161]
	v_mfma_f32_16x16x32_bf16 v[124:127], v[76:79], v[92:95], v[124:127]
	v_mfma_f32_16x16x32_bf16 v[154:157], v[68:71], v[192:195], v[154:157]
	v_mfma_f32_16x16x32_bf16 v[112:115], v[76:79], v[192:195], v[112:115]
	v_mfma_f32_16x16x32_bf16 v[150:153], v[68:71], v[200:203], v[150:153]
	v_mfma_f32_16x16x32_bf16 v[120:123], v[76:79], v[200:203], v[120:123]
	s_setprio 0
	s_barrier
	s_add_i32 s27, 0, 0x14000
	v_add_u32_e32 v168, s27, v217
	s_add_i32 s56, s57, s74
	ds_read_b128 v[204:207], v168
	ds_read_b128 v[222:225], v168 offset:1024
	ds_read_b128 v[228:231], v168 offset:2048
	ds_read_b128 v[232:235], v168 offset:3072
	v_lshl_add_u64 v[168:169], s[82:83], 0, v[144:145]
	s_mov_b32 m0, s56
	v_lshl_add_u64 v[176:177], s[82:83], 0, v[162:163]
	global_load_lds_dwordx4 v[168:169], off
	s_add_i32 m0, s56, 0x2000
	s_nop 0
	global_load_lds_dwordx4 v[176:177], off
	s_barrier
	s_waitcnt lgkmcnt(0)
	s_setprio 1
	s_waitcnt lgkmcnt(0)
	v_mfma_f32_16x16x32_bf16 v[140:143], v[204:207], v[80:83], v[140:143]
	v_mfma_f32_16x16x32_bf16 v[80:83], v[228:231], v[80:83], v[108:111]
	v_mfma_f32_16x16x32_bf16 v[140:143], v[222:225], v[84:87], v[140:143]
	v_mfma_f32_16x16x32_bf16 v[80:83], v[232:235], v[84:87], v[80:83]
	v_mfma_f32_16x16x32_bf16 v[84:87], v[204:207], v[88:91], v[136:139]
	v_mfma_f32_16x16x32_bf16 v[88:91], v[228:231], v[88:91], v[104:107]
	v_mfma_f32_16x16x32_bf16 v[100:103], v[228:231], v[188:191], v[100:103]
	v_mfma_f32_16x16x32_bf16 v[104:107], v[204:207], v[196:199], v[128:131]
	v_mfma_f32_16x16x32_bf16 v[96:99], v[228:231], v[196:199], v[96:99]
	v_mfma_f32_16x16x32_bf16 v[84:87], v[222:225], v[92:95], v[84:87]
	v_mfma_f32_16x16x32_bf16 v[88:91], v[232:235], v[92:95], v[88:91]
	v_mfma_f32_16x16x32_bf16 v[92:95], v[204:207], v[188:191], v[132:135]
	v_mfma_f32_16x16x32_bf16 v[100:103], v[232:235], v[192:195], v[100:103]
	v_mfma_f32_16x16x32_bf16 v[128:131], v[222:225], v[200:203], v[104:107]
	v_mfma_f32_16x16x32_bf16 v[96:99], v[232:235], v[200:203], v[96:99]
	v_mfma_f32_16x16x32_bf16 v[92:95], v[222:225], v[192:195], v[92:95]
	s_setprio 0
	s_mov_b32 m0, s75
	v_lshl_add_u64 v[240:241], vcc, 0, v[144:145]
	s_barrier
	ds_read_b128 v[104:107], v220 offset:16384
	ds_read_b128 v[108:111], v220 offset:17408
	ds_read_b128 v[132:135], v220 offset:18432
	ds_read_b128 v[136:139], v220 offset:19456
	ds_read_b128 v[188:191], v220 offset:20480
	ds_read_b128 v[192:195], v220 offset:21504
	ds_read_b128 v[196:199], v220 offset:22528
	ds_read_b128 v[200:203], v220 offset:23552
	global_load_lds_dwordx4 v[240:241], off
	v_lshl_add_u64 v[242:243], vcc, 0, v[162:163]
	s_mov_b32 m0, s85
	s_nop 0
	global_load_lds_dwordx4 v[242:243], off
	s_barrier
	s_waitcnt lgkmcnt(0)
	s_setprio 1
	s_waitcnt lgkmcnt(0)
	v_mfma_f32_16x16x32_bf16 v[48:51], v[64:67], v[104:107], v[48:51]
	v_mfma_f32_16x16x32_bf16 v[20:23], v[72:75], v[104:107], v[20:23]
	v_mfma_f32_16x16x32_bf16 v[60:63], v[64:67], v[132:135], v[60:63]
	v_mfma_f32_16x16x32_bf16 v[28:31], v[72:75], v[132:135], v[28:31]
	v_mfma_f32_16x16x32_bf16 v[56:59], v[64:67], v[188:191], v[56:59]
	v_mfma_f32_16x16x32_bf16 v[16:19], v[72:75], v[188:191], v[16:19]
	v_mfma_f32_16x16x32_bf16 v[52:55], v[64:67], v[196:199], v[52:55]
	v_mfma_f32_16x16x32_bf16 v[24:27], v[72:75], v[196:199], v[24:27]
	v_mfma_f32_16x16x32_bf16 v[48:51], v[68:71], v[108:111], v[48:51]
	v_mfma_f32_16x16x32_bf16 v[20:23], v[76:79], v[108:111], v[20:23]
	v_mfma_f32_16x16x32_bf16 v[60:63], v[68:71], v[136:139], v[60:63]
	v_mfma_f32_16x16x32_bf16 v[28:31], v[76:79], v[136:139], v[28:31]
	v_mfma_f32_16x16x32_bf16 v[56:59], v[68:71], v[192:195], v[56:59]
	v_mfma_f32_16x16x32_bf16 v[16:19], v[76:79], v[192:195], v[16:19]
	v_mfma_f32_16x16x32_bf16 v[52:55], v[68:71], v[200:203], v[52:55]
	v_mfma_f32_16x16x32_bf16 v[24:27], v[76:79], v[200:203], v[24:27]
	s_setprio 0
	s_barrier
	s_add_u32 s56, s82, 0x40000
	s_addc_u32 s57, s83, 0
	s_add_i32 s27, s27, s74
	v_lshl_add_u64 v[64:65], s[56:57], 0, v[144:145]
	s_mov_b32 m0, s27
	s_nop 0
	global_load_lds_dwordx4 v[64:65], off
	v_lshl_add_u64 v[64:65], s[56:57], 0, v[162:163]
	s_add_i32 m0, s27, 0x2000
	s_nop 0
	global_load_lds_dwordx4 v[64:65], off
	s_waitcnt vmcnt(6)
	s_barrier
	s_setprio 1
	v_mfma_f32_16x16x32_bf16 v[44:47], v[204:207], v[104:107], v[44:47]
	v_mfma_f32_16x16x32_bf16 v[12:15], v[228:231], v[104:107], v[12:15]
	v_mfma_f32_16x16x32_bf16 v[40:43], v[204:207], v[132:135], v[40:43]
	v_mfma_f32_16x16x32_bf16 v[8:11], v[228:231], v[132:135], v[8:11]
	v_mfma_f32_16x16x32_bf16 v[36:39], v[204:207], v[188:191], v[36:39]
	v_mfma_f32_16x16x32_bf16 v[4:7], v[228:231], v[188:191], v[4:7]
	v_mfma_f32_16x16x32_bf16 v[32:35], v[204:207], v[196:199], v[32:35]
	v_mfma_f32_16x16x32_bf16 v[0:3], v[228:231], v[196:199], v[0:3]
	v_mfma_f32_16x16x32_bf16 v[44:47], v[222:225], v[108:111], v[44:47]
	v_mfma_f32_16x16x32_bf16 v[12:15], v[232:235], v[108:111], v[12:15]
	v_mfma_f32_16x16x32_bf16 v[40:43], v[222:225], v[136:139], v[40:43]
	v_mfma_f32_16x16x32_bf16 v[8:11], v[232:235], v[136:139], v[8:11]
	v_mfma_f32_16x16x32_bf16 v[36:39], v[222:225], v[192:195], v[36:39]
	v_mfma_f32_16x16x32_bf16 v[4:7], v[232:235], v[192:195], v[4:7]
	v_mfma_f32_16x16x32_bf16 v[32:35], v[222:225], v[200:203], v[32:35]
	v_mfma_f32_16x16x32_bf16 v[0:3], v[232:235], v[200:203], v[0:3]
	s_setprio 0
	s_add_i32 s27, 0, 0x18000
	v_add_u32_e32 v76, s27, v217
	s_barrier
	ds_read_b128 v[64:67], v76
	ds_read_b128 v[68:71], v76 offset:1024
	ds_read_b128 v[72:75], v76 offset:2048
	ds_read_b128 v[76:79], v76 offset:3072
	s_add_u32 s56, vcc_lo, 0x40000
	s_addc_u32 s57, vcc_hi, 0
	s_mov_b32 m0, s98
	v_lshl_add_u64 v[136:137], s[56:57], 0, v[144:145]
	ds_read_b128 v[104:107], v220 offset:32768
	ds_read_b128 v[108:111], v220 offset:33792
	ds_read_b128 v[132:135], v220 offset:34816
	ds_read_b128 v[188:191], v220 offset:35840
	ds_read_b128 v[192:195], v220 offset:36864
	ds_read_b128 v[196:199], v220 offset:37888
	ds_read_b128 v[200:203], v220 offset:38912
	ds_read_b128 v[204:207], v220 offset:39936
	global_load_lds_dwordx4 v[136:137], off
	v_lshl_add_u64 v[136:137], s[56:57], 0, v[162:163]
	s_mov_b32 m0, s29
	s_nop 0
	global_load_lds_dwordx4 v[136:137], off
	s_waitcnt lgkmcnt(8)
	s_barrier
	s_waitcnt lgkmcnt(0)
	s_setprio 1
	s_waitcnt lgkmcnt(0)
	v_mfma_f32_16x16x32_bf16 v[136:139], v[64:67], v[104:107], v[146:149]
	v_mfma_f32_16x16x32_bf16 v[146:149], v[68:71], v[108:111], v[136:139]
	v_mfma_f32_16x16x32_bf16 v[136:139], v[64:67], v[132:135], v[158:161]
	v_mfma_f32_16x16x32_bf16 v[158:161], v[68:71], v[188:191], v[136:139]
	v_mfma_f32_16x16x32_bf16 v[136:139], v[64:67], v[192:195], v[154:157]
	v_mfma_f32_16x16x32_bf16 v[116:119], v[72:75], v[104:107], v[116:119]
	v_mfma_f32_16x16x32_bf16 v[124:127], v[72:75], v[132:135], v[124:127]
	v_mfma_f32_16x16x32_bf16 v[154:157], v[68:71], v[196:199], v[136:139]
	v_mfma_f32_16x16x32_bf16 v[112:115], v[72:75], v[192:195], v[112:115]
	v_mfma_f32_16x16x32_bf16 v[136:139], v[64:67], v[200:203], v[150:153]
	v_mfma_f32_16x16x32_bf16 v[120:123], v[72:75], v[200:203], v[120:123]
	v_mfma_f32_16x16x32_bf16 v[116:119], v[76:79], v[108:111], v[116:119]
	v_mfma_f32_16x16x32_bf16 v[124:127], v[76:79], v[188:191], v[124:127]
	v_mfma_f32_16x16x32_bf16 v[112:115], v[76:79], v[196:199], v[112:115]
	v_mfma_f32_16x16x32_bf16 v[150:153], v[68:71], v[204:207], v[136:139]
	v_mfma_f32_16x16x32_bf16 v[120:123], v[76:79], v[204:207], v[120:123]
	s_setprio 0
	s_barrier
	s_add_i32 s58, 0, 0x1c000
	v_add_u32_e32 v136, s58, v217
	s_add_i32 s27, s27, s74
	ds_read_b128 v[222:225], v136
	ds_read_b128 v[228:231], v136 offset:1024
	ds_read_b128 v[232:235], v136 offset:2048
	ds_read_b128 v[236:239], v136 offset:3072
	v_lshl_add_u64 v[136:137], v[168:169], 0, s[18:19]
	s_mov_b32 m0, s27
	s_nop 0
	global_load_lds_dwordx4 v[136:137], off
	v_lshl_add_u64 v[136:137], v[176:177], 0, s[18:19]
	s_add_i32 m0, s27, 0x2000
	s_nop 0
	global_load_lds_dwordx4 v[136:137], off
	s_barrier
	s_waitcnt lgkmcnt(0)
	s_setprio 1
	s_waitcnt lgkmcnt(0)
	v_mfma_f32_16x16x32_bf16 v[136:139], v[222:225], v[104:107], v[140:143]
	v_mfma_f32_16x16x32_bf16 v[80:83], v[232:235], v[104:107], v[80:83]
	v_mfma_f32_16x16x32_bf16 v[140:143], v[228:231], v[108:111], v[136:139]
	v_mfma_f32_16x16x32_bf16 v[108:111], v[236:239], v[108:111], v[80:83]
	v_mfma_f32_16x16x32_bf16 v[80:83], v[222:225], v[132:135], v[84:87]
	v_mfma_f32_16x16x32_bf16 v[136:139], v[228:231], v[188:191], v[80:83]
	v_mfma_f32_16x16x32_bf16 v[80:83], v[232:235], v[132:135], v[88:91]
	v_mfma_f32_16x16x32_bf16 v[104:107], v[236:239], v[188:191], v[80:83]
	v_mfma_f32_16x16x32_bf16 v[80:83], v[222:225], v[192:195], v[92:95]
	v_mfma_f32_16x16x32_bf16 v[132:135], v[228:231], v[196:199], v[80:83]
	v_mfma_f32_16x16x32_bf16 v[80:83], v[232:235], v[192:195], v[100:103]
	v_mfma_f32_16x16x32_bf16 v[100:103], v[236:239], v[196:199], v[80:83]
	v_mfma_f32_16x16x32_bf16 v[80:83], v[222:225], v[200:203], v[128:131]
	v_mfma_f32_16x16x32_bf16 v[128:131], v[228:231], v[204:207], v[80:83]
	v_mfma_f32_16x16x32_bf16 v[80:83], v[232:235], v[200:203], v[96:99]
	v_mfma_f32_16x16x32_bf16 v[96:99], v[236:239], v[204:207], v[80:83]
	s_setprio 0
	s_mov_b32 m0, s31
	v_lshl_add_u64 v[168:169], v[240:241], 0, s[18:19]
	s_barrier
	s_nop 2
	ds_read_b128 v[80:83], v220 offset:49152
	ds_read_b128 v[84:87], v220 offset:50176
	ds_read_b128 v[88:91], v220 offset:51200
	ds_read_b128 v[92:95], v220 offset:52224
	ds_read_b128 v[188:191], v220 offset:53248
	ds_read_b128 v[192:195], v220 offset:54272
	ds_read_b128 v[196:199], v220 offset:55296
	ds_read_b128 v[200:203], v220 offset:56320
	global_load_lds_dwordx4 v[168:169], off
	v_lshl_add_u64 v[168:169], v[242:243], 0, s[18:19]
	s_mov_b32 m0, s34
	s_nop 0
	global_load_lds_dwordx4 v[168:169], off
	s_barrier
	s_waitcnt lgkmcnt(0)
	s_setprio 1
	s_waitcnt lgkmcnt(0)
	v_mfma_f32_16x16x32_bf16 v[48:51], v[64:67], v[80:83], v[48:51]
	v_mfma_f32_16x16x32_bf16 v[20:23], v[72:75], v[80:83], v[20:23]
	v_mfma_f32_16x16x32_bf16 v[60:63], v[64:67], v[88:91], v[60:63]
	v_mfma_f32_16x16x32_bf16 v[28:31], v[72:75], v[88:91], v[28:31]
	v_mfma_f32_16x16x32_bf16 v[56:59], v[64:67], v[188:191], v[56:59]
	v_mfma_f32_16x16x32_bf16 v[16:19], v[72:75], v[188:191], v[16:19]
	v_mfma_f32_16x16x32_bf16 v[52:55], v[64:67], v[196:199], v[52:55]
	v_mfma_f32_16x16x32_bf16 v[24:27], v[72:75], v[196:199], v[24:27]
	v_mfma_f32_16x16x32_bf16 v[48:51], v[68:71], v[84:87], v[48:51]
	v_mfma_f32_16x16x32_bf16 v[20:23], v[76:79], v[84:87], v[20:23]
	v_mfma_f32_16x16x32_bf16 v[60:63], v[68:71], v[92:95], v[60:63]
	v_mfma_f32_16x16x32_bf16 v[28:31], v[76:79], v[92:95], v[28:31]
	v_mfma_f32_16x16x32_bf16 v[56:59], v[68:71], v[192:195], v[56:59]
	v_mfma_f32_16x16x32_bf16 v[16:19], v[76:79], v[192:195], v[16:19]
	v_mfma_f32_16x16x32_bf16 v[52:55], v[68:71], v[200:203], v[52:55]
	v_mfma_f32_16x16x32_bf16 v[24:27], v[76:79], v[200:203], v[24:27]
	s_setprio 0
	s_barrier
	s_add_u32 s56, s82, 0x40080
	s_addc_u32 s57, s83, 0
	s_add_i32 s27, s58, s74
	v_lshl_add_u64 v[64:65], s[56:57], 0, v[144:145]
	s_mov_b32 m0, s27
	s_nop 0
	global_load_lds_dwordx4 v[64:65], off
	v_lshl_add_u64 v[64:65], s[56:57], 0, v[162:163]
	s_add_i32 m0, s27, 0x2000
	s_nop 0
	global_load_lds_dwordx4 v[64:65], off
	s_waitcnt vmcnt(6)
	s_barrier
	s_setprio 1
	v_mfma_f32_16x16x32_bf16 v[44:47], v[222:225], v[80:83], v[44:47]
	v_mfma_f32_16x16x32_bf16 v[12:15], v[232:235], v[80:83], v[12:15]
	v_mfma_f32_16x16x32_bf16 v[40:43], v[222:225], v[88:91], v[40:43]
	v_mfma_f32_16x16x32_bf16 v[8:11], v[232:235], v[88:91], v[8:11]
	v_mfma_f32_16x16x32_bf16 v[36:39], v[222:225], v[188:191], v[36:39]
	v_mfma_f32_16x16x32_bf16 v[4:7], v[232:235], v[188:191], v[4:7]
	v_mfma_f32_16x16x32_bf16 v[32:35], v[222:225], v[196:199], v[32:35]
	v_mfma_f32_16x16x32_bf16 v[0:3], v[232:235], v[196:199], v[0:3]
	v_mfma_f32_16x16x32_bf16 v[44:47], v[228:231], v[84:87], v[44:47]
	v_mfma_f32_16x16x32_bf16 v[12:15], v[236:239], v[84:87], v[12:15]
	v_mfma_f32_16x16x32_bf16 v[40:43], v[228:231], v[92:95], v[40:43]
	v_mfma_f32_16x16x32_bf16 v[8:11], v[236:239], v[92:95], v[8:11]
	v_mfma_f32_16x16x32_bf16 v[36:39], v[228:231], v[192:195], v[36:39]
	v_mfma_f32_16x16x32_bf16 v[4:7], v[236:239], v[192:195], v[4:7]
	v_mfma_f32_16x16x32_bf16 v[32:35], v[228:231], v[200:203], v[32:35]
	v_mfma_f32_16x16x32_bf16 v[0:3], v[236:239], v[200:203], v[0:3]
	s_setprio 0
	s_add_i32 s37, s37, 2
	s_add_u32 s86, s86, 0x100
	s_addc_u32 s87, s87, 0
	s_add_u32 s33, s33, 0x100
	s_addc_u32 s36, s36, 0
	s_cmp_gt_u32 s37, 13
	s_barrier
	s_cbranch_scc0 .LBB0_125
	s_lshl_b32 s1, s84, 8
	v_readlane_b32 s10, v254, 61
	s_add_i32 s1, s1, s10
	v_or_b32_e32 v198, s1, v216
	v_ashrrev_i32_e32 v199, 31, v198
	v_lshl_add_u64 v[64:65], v[198:199], 3, s[48:49]
	global_load_dwordx2 v[176:177], v[64:65], off
	global_load_dwordx2 v[202:203], v[64:65], off offset:128
	global_load_dwordx2 v[206:207], v[64:65], off offset:256
	global_load_dwordx2 v[222:223], v[64:65], off offset:384
	s_add_i32 s10, s1, 0x80
	v_or_b32_e32 v168, s10, v216
	v_ashrrev_i32_e32 v169, 31, v168
	v_lshl_or_b32 v188, s0, 7, v219
	v_lshl_add_u64 v[64:65], v[168:169], 3, s[48:49]
	v_ashrrev_i32_e32 v189, 31, v188
	v_lshlrev_b64 v[190:191], 2, v[188:189]
	v_lshl_add_u64 v[68:69], s[68:69], 0, v[190:191]
	v_lshl_add_u64 v[70:71], s[60:61], 0, v[190:191]
	v_lshl_add_u64 v[84:85], s[64:65], 0, v[190:191]
	v_lshl_add_u64 v[86:87], s[70:71], 0, v[190:191]
	global_load_dwordx2 v[200:201], v[64:65], off
	global_load_dwordx2 v[196:197], v[64:65], off offset:128
	global_load_dwordx2 v[194:195], v[64:65], off offset:256
	global_load_dwordx2 v[192:193], v[64:65], off offset:384
	s_nop 0
	global_load_dwordx4 v[64:67], v[68:69], off offset:16
	global_load_dwordx4 v[80:83], v[68:69], off
	global_load_dwordx4 v[72:75], v[70:71], off offset:16
	global_load_dwordx4 v[88:91], v[70:71], off
	global_load_dwordx4 v[76:79], v[84:85], off offset:16
	global_load_dwordx4 v[92:95], v[84:85], off
	s_nop 0
	global_load_dwordx4 v[68:71], v[86:87], off offset:16
	s_nop 0
	global_load_dwordx4 v[84:87], v[86:87], off
	s_ashr_i32 s11, s1, 5
	s_movk_i32 s10, 0xb00
	s_movk_i32 s20, 0x1600
	v_cmp_eq_u32_e64 s[36:37], 15, v216
	s_waitcnt vmcnt(8)
	v_ffbh_u32_e32 v224, v177
	v_ffbh_u32_e32 v225, v203
	v_ffbh_u32_e32 v226, v207
	v_ffbh_u32_e32 v227, v223
	v_ffbh_u32_e32 v228, v201
	v_ffbh_u32_e32 v229, v197
	v_ffbh_u32_e32 v230, v195
	v_ffbh_u32_e32 v231, v193
	v_min_u32_e32 v224, 32, v224
	v_min_u32_e32 v225, 32, v225
	v_min_u32_e32 v226, 32, v226
	v_min_u32_e32 v227, 32, v227
	v_min_u32_e32 v228, 32, v228
	v_min_u32_e32 v229, 32, v229
	v_min_u32_e32 v230, 32, v230
	v_min_u32_e32 v231, 32, v231
	v_lshlrev_b64 v[176:177], v224, v[176:177]
	v_lshlrev_b64 v[202:203], v225, v[202:203]
	v_lshlrev_b64 v[206:207], v226, v[206:207]
	v_lshlrev_b64 v[222:223], v227, v[222:223]
	v_lshlrev_b64 v[200:201], v228, v[200:201]
	v_lshlrev_b64 v[196:197], v229, v[196:197]
	v_lshlrev_b64 v[194:195], v230, v[194:195]
	v_lshlrev_b64 v[192:193], v231, v[192:193]
	v_min_u32_e32 v176, 1, v176
	v_min_u32_e32 v202, 1, v202
	v_min_u32_e32 v206, 1, v206
	v_min_u32_e32 v222, 1, v222
	v_min_u32_e32 v200, 1, v200
	v_min_u32_e32 v196, 1, v196
	v_min_u32_e32 v194, 1, v194
	v_min_u32_e32 v192, 1, v192
	v_or_b32_e32 v176, v177, v176
	v_or_b32_e32 v202, v203, v202
	v_or_b32_e32 v206, v207, v206
	v_or_b32_e32 v222, v223, v222
	v_or_b32_e32 v200, v201, v200
	v_or_b32_e32 v196, v197, v196
	v_or_b32_e32 v194, v195, v194
	v_or_b32_e32 v192, v193, v192
	v_cvt_f32_u32_e32 v176, v176
	v_cvt_f32_u32_e32 v202, v202
	v_cvt_f32_u32_e32 v206, v206
	v_cvt_f32_u32_e32 v222, v222
	v_cvt_f32_u32_e32 v200, v200
	v_cvt_f32_u32_e32 v196, v196
	v_cvt_f32_u32_e32 v194, v194
	v_cvt_f32_u32_e32 v192, v192
	v_sub_u32_e32 v224, 32, v224
	v_sub_u32_e32 v225, 32, v225
	v_sub_u32_e32 v226, 32, v226
	v_sub_u32_e32 v227, 32, v227
	v_sub_u32_e32 v228, 32, v228
	v_sub_u32_e32 v229, 32, v229
	v_sub_u32_e32 v230, 32, v230
	v_sub_u32_e32 v231, 32, v231
	v_ldexp_f32 v176, v176, v224
	v_ldexp_f32 v202, v202, v225
	v_ldexp_f32 v206, v206, v226
	v_ldexp_f32 v222, v222, v227
	v_ldexp_f32 v200, v200, v228
	v_ldexp_f32 v196, v196, v229
	v_ldexp_f32 v194, v194, v230
	v_ldexp_f32 v192, v192, v231
	v_mul_f32_e32 v176, 0x35800000, v176
	v_mul_f32_e32 v202, 0x35800000, v202
	v_mul_f32_e32 v206, 0x35800000, v206
	v_mul_f32_e32 v222, 0x35800000, v222
	v_mul_f32_e32 v200, 0x35800000, v200
	v_mul_f32_e32 v196, 0x35800000, v196
	v_mul_f32_e32 v194, 0x35800000, v194
	v_mul_f32_e32 v192, 0x35800000, v192
	v_fmamk_f32 v176, v176, 0x3a800000, v210
	v_fmamk_f32 v202, v202, 0x3a800000, v210
	v_fmamk_f32 v206, v206, 0x3a800000, v210
	v_fmamk_f32 v222, v222, 0x3a800000, v210
	v_fmamk_f32 v200, v200, 0x3a800000, v210
	v_fmamk_f32 v196, v196, 0x3a800000, v210
	v_fmamk_f32 v194, v194, 0x3a800000, v210
	v_fmamk_f32 v192, v192, 0x3a800000, v210
	v_rsq_f32_e32 v244, v176
	v_rsq_f32_e32 v245, v202
	v_rsq_f32_e32 v246, v206
	v_rsq_f32_e32 v247, v222
	v_rsq_f32_e32 v248, v200
	v_rsq_f32_e32 v249, v196
	v_rsq_f32_e32 v250, v194
	v_rsq_f32_e32 v251, v192
	s_waitcnt vmcnt(0)
	v_mul_f32_e32 v146, v146, v244
	v_mul_f32_e32 v158, v158, v245
	v_mul_f32_e32 v154, v154, v246
	v_mul_f32_e32 v150, v150, v247
	v_mul_f32_e32 v147, v147, v244
	v_mul_f32_e32 v159, v159, v245
	v_mul_f32_e32 v155, v155, v246
	v_mul_f32_e32 v151, v151, v247
	v_cndmask_b32_e64 v221, v146, 0, s[36:37]
	v_cndmask_b32_e64 v225, v146, 0, s[44:45]
	v_cndmask_b32_e64 v222, v158, v146, s[36:37]
	v_cndmask_b32_e64 v226, v158, v146, s[44:45]
	v_cndmask_b32_e64 v223, v154, v158, s[36:37]
	v_cndmask_b32_e64 v227, v154, v158, s[44:45]
	v_cndmask_b32_e64 v224, v150, v154, s[36:37]
	v_cndmask_b32_e64 v228, v150, v154, s[44:45]
	v_cndmask_b32_e64 v232, v147, 0, s[36:37]
	v_cndmask_b32_e64 v236, v147, 0, s[44:45]
	v_cndmask_b32_e64 v233, v159, v147, s[36:37]
	v_cndmask_b32_e64 v237, v159, v147, s[44:45]
	v_cndmask_b32_e64 v234, v155, v159, s[36:37]
	v_cndmask_b32_e64 v238, v155, v159, s[44:45]
	v_cndmask_b32_e64 v235, v151, v155, s[36:37]
	v_cndmask_b32_e64 v239, v151, v155, s[44:45]
	v_fma_f32 v200, v92, v146, v84
	v_fma_f32 v229, v92, v158, v84
	v_fma_f32 v230, v92, v154, v84
	v_fma_f32 v231, v92, v150, v84
	v_fma_f32 v201, v93, v147, v85
	v_fma_f32 v196, v93, v159, v85
	v_fma_f32 v197, v93, v155, v85
	v_fma_f32 v176, v93, v151, v85
	v_fmac_f32_dpp v200, v221, v88 row_ror:1 row_mask:0xf bank_mask:0xf
	v_fmac_f32_dpp v229, v222, v88 row_ror:1 row_mask:0xf bank_mask:0xf
	v_fmac_f32_dpp v230, v223, v88 row_ror:1 row_mask:0xf bank_mask:0xf
	v_fmac_f32_dpp v231, v224, v88 row_ror:1 row_mask:0xf bank_mask:0xf
	v_fmac_f32_dpp v201, v232, v89 row_ror:1 row_mask:0xf bank_mask:0xf
	v_fmac_f32_dpp v196, v233, v89 row_ror:1 row_mask:0xf bank_mask:0xf
	v_fmac_f32_dpp v197, v234, v89 row_ror:1 row_mask:0xf bank_mask:0xf
	v_fmac_f32_dpp v176, v235, v89 row_ror:1 row_mask:0xf bank_mask:0xf
	v_fmac_f32_dpp v200, v225, v80 row_ror:2 row_mask:0xf bank_mask:0xf
	v_fmac_f32_dpp v229, v226, v80 row_ror:2 row_mask:0xf bank_mask:0xf
	v_fmac_f32_dpp v230, v227, v80 row_ror:2 row_mask:0xf bank_mask:0xf
	v_fmac_f32_dpp v231, v228, v80 row_ror:2 row_mask:0xf bank_mask:0xf
	v_fmac_f32_dpp v201, v236, v81 row_ror:2 row_mask:0xf bank_mask:0xf
	v_fmac_f32_dpp v196, v237, v81 row_ror:2 row_mask:0xf bank_mask:0xf
	v_fmac_f32_dpp v197, v238, v81 row_ror:2 row_mask:0xf bank_mask:0xf
	v_fmac_f32_dpp v176, v239, v81 row_ror:2 row_mask:0xf bank_mask:0xf
	v_mul_f32_e32 v221, 0xbfb8aa3b, v200
	v_mul_f32_e32 v222, 0xbfb8aa3b, v229
	v_mul_f32_e32 v223, 0xbfb8aa3b, v230
	v_mul_f32_e32 v224, 0xbfb8aa3b, v231
	v_mul_f32_e32 v232, 0xbfb8aa3b, v201
	v_mul_f32_e32 v233, 0xbfb8aa3b, v196
	v_mul_f32_e32 v234, 0xbfb8aa3b, v197
	v_mul_f32_e32 v235, 0xbfb8aa3b, v176
	v_exp_f32_e32 v221, v221
	v_exp_f32_e32 v222, v222
	v_exp_f32_e32 v223, v223
	v_exp_f32_e32 v224, v224
	v_exp_f32_e32 v232, v232
	v_exp_f32_e32 v233, v233
	v_exp_f32_e32 v234, v234
	v_exp_f32_e32 v235, v235
	v_add_f32_e32 v221, 1.0, v221
	v_add_f32_e32 v222, 1.0, v222
	v_add_f32_e32 v223, 1.0, v223
	v_add_f32_e32 v224, 1.0, v224
	v_add_f32_e32 v232, 1.0, v232
	v_add_f32_e32 v233, 1.0, v233
	v_add_f32_e32 v234, 1.0, v234
	v_add_f32_e32 v235, 1.0, v235
	v_rcp_f32_e32 v221, v221
	v_rcp_f32_e32 v222, v222
	v_rcp_f32_e32 v223, v223
	v_rcp_f32_e32 v224, v224
	v_rcp_f32_e32 v232, v232
	v_rcp_f32_e32 v233, v233
	v_rcp_f32_e32 v234, v234
	v_rcp_f32_e32 v235, v235
	v_mul_f32_e32 v221, v200, v221
	v_mul_f32_e32 v222, v229, v222
	v_mul_f32_e32 v223, v230, v223
	v_mul_f32_e32 v224, v231, v224
	v_mul_f32_e32 v232, v201, v232
	v_mul_f32_e32 v233, v196, v233
	v_mul_f32_e32 v234, v197, v234
	v_mul_f32_e32 v235, v176, v235
	v_mul_f32_e32 v192, v140, v244
	v_mul_f32_e32 v136, v136, v245
	v_mul_f32_e32 v132, v132, v246
	v_mul_f32_e32 v128, v128, v247
	v_mul_f32_e32 v193, v141, v244
	v_mul_f32_e32 v137, v137, v245
	v_mul_f32_e32 v133, v133, v246
	v_mul_f32_e32 v129, v129, v247
	v_mul_f32_e32 v140, v221, v192
	v_mul_f32_e32 v136, v222, v136
	v_mul_f32_e32 v132, v223, v132
	v_mul_f32_e32 v128, v224, v128
	v_mul_f32_e32 v141, v232, v193
	v_mul_f32_e32 v137, v233, v137
	v_mul_f32_e32 v133, v234, v133
	v_mul_f32_e32 v129, v235, v129
	v_mul_f32_e32 v148, v148, v244
	v_mul_f32_e32 v160, v160, v245
	v_mul_f32_e32 v156, v156, v246
	v_mul_f32_e32 v152, v152, v247
	v_mul_f32_e32 v149, v149, v244
	v_mul_f32_e32 v161, v161, v245
	v_mul_f32_e32 v157, v157, v246
	v_mul_f32_e32 v153, v153, v247
	v_cndmask_b32_e64 v221, v148, 0, s[36:37]
	v_cndmask_b32_e64 v225, v148, 0, s[44:45]
	v_cndmask_b32_e64 v222, v160, v148, s[36:37]
	v_cndmask_b32_e64 v226, v160, v148, s[44:45]
	v_cndmask_b32_e64 v223, v156, v160, s[36:37]
	v_cndmask_b32_e64 v227, v156, v160, s[44:45]
	v_cndmask_b32_e64 v224, v152, v156, s[36:37]
	v_cndmask_b32_e64 v228, v152, v156, s[44:45]
	v_cndmask_b32_e64 v232, v149, 0, s[36:37]
	v_cndmask_b32_e64 v236, v149, 0, s[44:45]
	v_cndmask_b32_e64 v233, v161, v149, s[36:37]
	v_cndmask_b32_e64 v237, v161, v149, s[44:45]
	v_cndmask_b32_e64 v234, v157, v161, s[36:37]
	v_cndmask_b32_e64 v238, v157, v161, s[44:45]
	v_cndmask_b32_e64 v235, v153, v157, s[36:37]
	v_cndmask_b32_e64 v239, v153, v157, s[44:45]
	v_fma_f32 v202, v94, v148, v86
	v_fma_f32 v229, v94, v160, v86
	v_fma_f32 v230, v94, v156, v86
	v_fma_f32 v231, v94, v152, v86
	v_fma_f32 v203, v95, v149, v87
	v_fma_f32 v196, v95, v161, v87
	v_fma_f32 v197, v95, v157, v87
	v_fma_f32 v176, v95, v153, v87
	v_fmac_f32_dpp v202, v221, v90 row_ror:1 row_mask:0xf bank_mask:0xf
	v_fmac_f32_dpp v229, v222, v90 row_ror:1 row_mask:0xf bank_mask:0xf
	v_fmac_f32_dpp v230, v223, v90 row_ror:1 row_mask:0xf bank_mask:0xf
	v_fmac_f32_dpp v231, v224, v90 row_ror:1 row_mask:0xf bank_mask:0xf
	v_fmac_f32_dpp v203, v232, v91 row_ror:1 row_mask:0xf bank_mask:0xf
	v_fmac_f32_dpp v196, v233, v91 row_ror:1 row_mask:0xf bank_mask:0xf
	v_fmac_f32_dpp v197, v234, v91 row_ror:1 row_mask:0xf bank_mask:0xf
	v_fmac_f32_dpp v176, v235, v91 row_ror:1 row_mask:0xf bank_mask:0xf
	v_fmac_f32_dpp v202, v225, v82 row_ror:2 row_mask:0xf bank_mask:0xf
	v_fmac_f32_dpp v229, v226, v82 row_ror:2 row_mask:0xf bank_mask:0xf
	v_fmac_f32_dpp v230, v227, v82 row_ror:2 row_mask:0xf bank_mask:0xf
	v_fmac_f32_dpp v231, v228, v82 row_ror:2 row_mask:0xf bank_mask:0xf
	v_fmac_f32_dpp v203, v236, v83 row_ror:2 row_mask:0xf bank_mask:0xf
	v_fmac_f32_dpp v196, v237, v83 row_ror:2 row_mask:0xf bank_mask:0xf
	v_fmac_f32_dpp v197, v238, v83 row_ror:2 row_mask:0xf bank_mask:0xf
	v_fmac_f32_dpp v176, v239, v83 row_ror:2 row_mask:0xf bank_mask:0xf
	v_mul_f32_e32 v221, 0xbfb8aa3b, v202
	v_mul_f32_e32 v222, 0xbfb8aa3b, v229
	v_mul_f32_e32 v223, 0xbfb8aa3b, v230
	v_mul_f32_e32 v224, 0xbfb8aa3b, v231
	v_mul_f32_e32 v232, 0xbfb8aa3b, v203
	v_mul_f32_e32 v233, 0xbfb8aa3b, v196
	v_mul_f32_e32 v234, 0xbfb8aa3b, v197
	v_mul_f32_e32 v235, 0xbfb8aa3b, v176
	v_exp_f32_e32 v221, v221
	v_exp_f32_e32 v222, v222
	v_exp_f32_e32 v223, v223
	v_exp_f32_e32 v224, v224
	v_exp_f32_e32 v232, v232
	v_exp_f32_e32 v233, v233
	v_exp_f32_e32 v234, v234
	v_exp_f32_e32 v235, v235
	v_add_f32_e32 v221, 1.0, v221
	v_add_f32_e32 v222, 1.0, v222
	v_add_f32_e32 v223, 1.0, v223
	v_add_f32_e32 v224, 1.0, v224
	v_add_f32_e32 v232, 1.0, v232
	v_add_f32_e32 v233, 1.0, v233
	v_add_f32_e32 v234, 1.0, v234
	v_add_f32_e32 v235, 1.0, v235
	v_rcp_f32_e32 v221, v221
	v_rcp_f32_e32 v222, v222
	v_rcp_f32_e32 v223, v223
	v_rcp_f32_e32 v224, v224
	v_rcp_f32_e32 v232, v232
	v_rcp_f32_e32 v233, v233
	v_rcp_f32_e32 v234, v234
	v_rcp_f32_e32 v235, v235
	v_mul_f32_e32 v221, v202, v221
	v_mul_f32_e32 v222, v229, v222
	v_mul_f32_e32 v223, v230, v223
	v_mul_f32_e32 v224, v231, v224
	v_mul_f32_e32 v232, v203, v232
	v_mul_f32_e32 v233, v196, v233
	v_mul_f32_e32 v234, v197, v234
	v_mul_f32_e32 v235, v176, v235
	v_mul_f32_e32 v194, v142, v244
	v_mul_f32_e32 v138, v138, v245
	v_mul_f32_e32 v134, v134, v246
	v_mul_f32_e32 v130, v130, v247
	v_mul_f32_e32 v195, v143, v244
	v_mul_f32_e32 v139, v139, v245
	v_mul_f32_e32 v135, v135, v246
	v_mul_f32_e32 v131, v131, v247
	v_mul_f32_e32 v142, v221, v194
	v_mul_f32_e32 v138, v222, v138
	v_mul_f32_e32 v134, v223, v134
	v_mul_f32_e32 v130, v224, v130
	v_mul_f32_e32 v143, v232, v195
	v_mul_f32_e32 v139, v233, v139
	v_mul_f32_e32 v135, v234, v135
	v_mul_f32_e32 v131, v235, v131
	v_mul_f32_e32 v116, v116, v244
	v_mul_f32_e32 v124, v124, v245
	v_mul_f32_e32 v112, v112, v246
	v_mul_f32_e32 v120, v120, v247
	v_mul_f32_e32 v117, v117, v244
	v_mul_f32_e32 v125, v125, v245
	v_mul_f32_e32 v113, v113, v246
	v_mul_f32_e32 v121, v121, v247
	v_cndmask_b32_e64 v221, v116, 0, s[36:37]
	v_cndmask_b32_e64 v225, v116, 0, s[44:45]
	v_cndmask_b32_e64 v222, v124, v116, s[36:37]
	v_cndmask_b32_e64 v226, v124, v116, s[44:45]
	v_cndmask_b32_e64 v223, v112, v124, s[36:37]
	v_cndmask_b32_e64 v227, v112, v124, s[44:45]
	v_cndmask_b32_e64 v224, v120, v112, s[36:37]
	v_cndmask_b32_e64 v228, v120, v112, s[44:45]
	v_cndmask_b32_e64 v232, v117, 0, s[36:37]
	v_cndmask_b32_e64 v236, v117, 0, s[44:45]
	v_cndmask_b32_e64 v233, v125, v117, s[36:37]
	v_cndmask_b32_e64 v237, v125, v117, s[44:45]
	v_cndmask_b32_e64 v234, v113, v125, s[36:37]
	v_cndmask_b32_e64 v238, v113, v125, s[44:45]
	v_cndmask_b32_e64 v235, v121, v113, s[36:37]
	v_cndmask_b32_e64 v239, v121, v113, s[44:45]
	v_fma_f32 v204, v76, v116, v68
	v_fma_f32 v229, v76, v124, v68
	v_fma_f32 v230, v76, v112, v68
	v_fma_f32 v231, v76, v120, v68
	v_fma_f32 v205, v77, v117, v69
	v_fma_f32 v196, v77, v125, v69
	v_fma_f32 v197, v77, v113, v69
	v_fma_f32 v176, v77, v121, v69
	v_fmac_f32_dpp v204, v221, v72 row_ror:1 row_mask:0xf bank_mask:0xf
	v_fmac_f32_dpp v229, v222, v72 row_ror:1 row_mask:0xf bank_mask:0xf
	v_fmac_f32_dpp v230, v223, v72 row_ror:1 row_mask:0xf bank_mask:0xf
	v_fmac_f32_dpp v231, v224, v72 row_ror:1 row_mask:0xf bank_mask:0xf
	v_fmac_f32_dpp v205, v232, v73 row_ror:1 row_mask:0xf bank_mask:0xf
	v_fmac_f32_dpp v196, v233, v73 row_ror:1 row_mask:0xf bank_mask:0xf
	v_fmac_f32_dpp v197, v234, v73 row_ror:1 row_mask:0xf bank_mask:0xf
	v_fmac_f32_dpp v176, v235, v73 row_ror:1 row_mask:0xf bank_mask:0xf
	v_fmac_f32_dpp v204, v225, v64 row_ror:2 row_mask:0xf bank_mask:0xf
	v_fmac_f32_dpp v229, v226, v64 row_ror:2 row_mask:0xf bank_mask:0xf
	v_fmac_f32_dpp v230, v227, v64 row_ror:2 row_mask:0xf bank_mask:0xf
	v_fmac_f32_dpp v231, v228, v64 row_ror:2 row_mask:0xf bank_mask:0xf
	v_fmac_f32_dpp v205, v236, v65 row_ror:2 row_mask:0xf bank_mask:0xf
	v_fmac_f32_dpp v196, v237, v65 row_ror:2 row_mask:0xf bank_mask:0xf
	v_fmac_f32_dpp v197, v238, v65 row_ror:2 row_mask:0xf bank_mask:0xf
	v_fmac_f32_dpp v176, v239, v65 row_ror:2 row_mask:0xf bank_mask:0xf
	v_mul_f32_e32 v221, 0xbfb8aa3b, v204
	v_mul_f32_e32 v222, 0xbfb8aa3b, v229
	v_mul_f32_e32 v223, 0xbfb8aa3b, v230
	v_mul_f32_e32 v224, 0xbfb8aa3b, v231
	v_mul_f32_e32 v232, 0xbfb8aa3b, v205
	v_mul_f32_e32 v233, 0xbfb8aa3b, v196
	v_mul_f32_e32 v234, 0xbfb8aa3b, v197
	v_mul_f32_e32 v235, 0xbfb8aa3b, v176
	v_exp_f32_e32 v221, v221
	v_exp_f32_e32 v222, v222
	v_exp_f32_e32 v223, v223
	v_exp_f32_e32 v224, v224
	v_exp_f32_e32 v232, v232
	v_exp_f32_e32 v233, v233
	v_exp_f32_e32 v234, v234
	v_exp_f32_e32 v235, v235
	v_add_f32_e32 v221, 1.0, v221
	v_add_f32_e32 v222, 1.0, v222
	v_add_f32_e32 v223, 1.0, v223
	v_add_f32_e32 v224, 1.0, v224
	v_add_f32_e32 v232, 1.0, v232
	v_add_f32_e32 v233, 1.0, v233
	v_add_f32_e32 v234, 1.0, v234
	v_add_f32_e32 v235, 1.0, v235
	v_rcp_f32_e32 v221, v221
	v_rcp_f32_e32 v222, v222
	v_rcp_f32_e32 v223, v223
	v_rcp_f32_e32 v224, v224
	v_rcp_f32_e32 v232, v232
	v_rcp_f32_e32 v233, v233
	v_rcp_f32_e32 v234, v234
	v_rcp_f32_e32 v235, v235
	v_mul_f32_e32 v221, v204, v221
	v_mul_f32_e32 v222, v229, v222
	v_mul_f32_e32 v223, v230, v223
	v_mul_f32_e32 v224, v231, v224
	v_mul_f32_e32 v232, v205, v232
	v_mul_f32_e32 v233, v196, v233
	v_mul_f32_e32 v234, v197, v234
	v_mul_f32_e32 v235, v176, v235
	v_mul_f32_e32 v240, v108, v244
	v_mul_f32_e32 v104, v104, v245
	v_mul_f32_e32 v100, v100, v246
	v_mul_f32_e32 v96, v96, v247
	v_mul_f32_e32 v241, v109, v244
	v_mul_f32_e32 v105, v105, v245
	v_mul_f32_e32 v101, v101, v246
	v_mul_f32_e32 v97, v97, v247
	v_mul_f32_e32 v108, v221, v240
	v_mul_f32_e32 v104, v222, v104
	v_mul_f32_e32 v100, v223, v100
	v_mul_f32_e32 v96, v224, v96
	v_mul_f32_e32 v109, v232, v241
	v_mul_f32_e32 v105, v233, v105
	v_mul_f32_e32 v101, v234, v101
	v_mul_f32_e32 v97, v235, v97
	v_mul_f32_e32 v118, v118, v244
	v_mul_f32_e32 v126, v126, v245
	v_mul_f32_e32 v114, v114, v246
	v_mul_f32_e32 v122, v122, v247
	v_mul_f32_e32 v119, v119, v244
	v_mul_f32_e32 v127, v127, v245
	v_mul_f32_e32 v115, v115, v246
	v_mul_f32_e32 v123, v123, v247
	v_cndmask_b32_e64 v221, v118, 0, s[36:37]
	v_cndmask_b32_e64 v225, v118, 0, s[44:45]
	v_cndmask_b32_e64 v222, v126, v118, s[36:37]
	v_cndmask_b32_e64 v226, v126, v118, s[44:45]
	v_cndmask_b32_e64 v223, v114, v126, s[36:37]
	v_cndmask_b32_e64 v227, v114, v126, s[44:45]
	v_cndmask_b32_e64 v224, v122, v114, s[36:37]
	v_cndmask_b32_e64 v228, v122, v114, s[44:45]
	v_cndmask_b32_e64 v232, v119, 0, s[36:37]
	v_cndmask_b32_e64 v236, v119, 0, s[44:45]
	v_cndmask_b32_e64 v233, v127, v119, s[36:37]
	v_cndmask_b32_e64 v237, v127, v119, s[44:45]
	v_cndmask_b32_e64 v234, v115, v127, s[36:37]
	v_cndmask_b32_e64 v238, v115, v127, s[44:45]
	v_cndmask_b32_e64 v235, v123, v115, s[36:37]
	v_cndmask_b32_e64 v239, v123, v115, s[44:45]
	v_fma_f32 v206, v78, v118, v70
	v_fma_f32 v229, v78, v126, v70
	v_fma_f32 v230, v78, v114, v70
	v_fma_f32 v231, v78, v122, v70
	v_fma_f32 v207, v79, v119, v71
	v_fma_f32 v196, v79, v127, v71
	v_fma_f32 v197, v79, v115, v71
	v_fma_f32 v176, v79, v123, v71
	v_fmac_f32_dpp v206, v221, v74 row_ror:1 row_mask:0xf bank_mask:0xf
	v_fmac_f32_dpp v229, v222, v74 row_ror:1 row_mask:0xf bank_mask:0xf
	v_fmac_f32_dpp v230, v223, v74 row_ror:1 row_mask:0xf bank_mask:0xf
	v_fmac_f32_dpp v231, v224, v74 row_ror:1 row_mask:0xf bank_mask:0xf
	v_fmac_f32_dpp v207, v232, v75 row_ror:1 row_mask:0xf bank_mask:0xf
	v_fmac_f32_dpp v196, v233, v75 row_ror:1 row_mask:0xf bank_mask:0xf
	v_fmac_f32_dpp v197, v234, v75 row_ror:1 row_mask:0xf bank_mask:0xf
	v_fmac_f32_dpp v176, v235, v75 row_ror:1 row_mask:0xf bank_mask:0xf
	v_fmac_f32_dpp v206, v225, v66 row_ror:2 row_mask:0xf bank_mask:0xf
	v_fmac_f32_dpp v229, v226, v66 row_ror:2 row_mask:0xf bank_mask:0xf
	v_fmac_f32_dpp v230, v227, v66 row_ror:2 row_mask:0xf bank_mask:0xf
	v_fmac_f32_dpp v231, v228, v66 row_ror:2 row_mask:0xf bank_mask:0xf
	v_fmac_f32_dpp v207, v236, v67 row_ror:2 row_mask:0xf bank_mask:0xf
	v_fmac_f32_dpp v196, v237, v67 row_ror:2 row_mask:0xf bank_mask:0xf
	v_fmac_f32_dpp v197, v238, v67 row_ror:2 row_mask:0xf bank_mask:0xf
	v_fmac_f32_dpp v176, v239, v67 row_ror:2 row_mask:0xf bank_mask:0xf
	v_mul_f32_e32 v221, 0xbfb8aa3b, v206
	v_mul_f32_e32 v222, 0xbfb8aa3b, v229
	v_mul_f32_e32 v223, 0xbfb8aa3b, v230
	v_mul_f32_e32 v224, 0xbfb8aa3b, v231
	v_mul_f32_e32 v232, 0xbfb8aa3b, v207
	v_mul_f32_e32 v233, 0xbfb8aa3b, v196
	v_mul_f32_e32 v234, 0xbfb8aa3b, v197
	v_mul_f32_e32 v235, 0xbfb8aa3b, v176
	v_exp_f32_e32 v221, v221
	v_exp_f32_e32 v222, v222
	v_exp_f32_e32 v223, v223
	v_exp_f32_e32 v224, v224
	v_exp_f32_e32 v232, v232
	v_exp_f32_e32 v233, v233
	v_exp_f32_e32 v234, v234
	v_exp_f32_e32 v235, v235
	v_add_f32_e32 v221, 1.0, v221
	v_add_f32_e32 v222, 1.0, v222
	v_add_f32_e32 v223, 1.0, v223
	v_add_f32_e32 v224, 1.0, v224
	v_add_f32_e32 v232, 1.0, v232
	v_add_f32_e32 v233, 1.0, v233
	v_add_f32_e32 v234, 1.0, v234
	v_add_f32_e32 v235, 1.0, v235
	v_rcp_f32_e32 v221, v221
	v_rcp_f32_e32 v222, v222
	v_rcp_f32_e32 v223, v223
	v_rcp_f32_e32 v224, v224
	v_rcp_f32_e32 v232, v232
	v_rcp_f32_e32 v233, v233
	v_rcp_f32_e32 v234, v234
	v_rcp_f32_e32 v235, v235
	v_mul_f32_e32 v221, v206, v221
	v_mul_f32_e32 v222, v229, v222
	v_mul_f32_e32 v223, v230, v223
	v_mul_f32_e32 v224, v231, v224
	v_mul_f32_e32 v232, v207, v232
	v_mul_f32_e32 v233, v196, v233
	v_mul_f32_e32 v234, v197, v234
	v_mul_f32_e32 v235, v176, v235
	v_mul_f32_e32 v242, v110, v244
	v_mul_f32_e32 v106, v106, v245
	v_mul_f32_e32 v102, v102, v246
	v_mul_f32_e32 v98, v98, v247
	v_mul_f32_e32 v243, v111, v244
	v_mul_f32_e32 v107, v107, v245
	v_mul_f32_e32 v103, v103, v246
	v_mul_f32_e32 v99, v99, v247
	v_mul_f32_e32 v110, v221, v242
	v_mul_f32_e32 v106, v222, v106
	v_mul_f32_e32 v102, v223, v102
	v_mul_f32_e32 v98, v224, v98
	v_mul_f32_e32 v111, v232, v243
	v_mul_f32_e32 v107, v233, v107
	v_mul_f32_e32 v103, v234, v103
	v_mul_f32_e32 v99, v235, v99
	v_cvt_pk_bf16_f32 v140, v140, v141
	v_cvt_pk_bf16_f32 v141, v142, v143
	v_cvt_pk_bf16_f32 v142, v108, v109
	v_cvt_pk_bf16_f32 v143, v110, v111
	v_cvt_pk_bf16_f32 v136, v136, v137
	v_cvt_pk_bf16_f32 v137, v138, v139
	v_cvt_pk_bf16_f32 v138, v104, v105
	v_cvt_pk_bf16_f32 v139, v106, v107
	v_cvt_pk_bf16_f32 v132, v132, v133
	v_cvt_pk_bf16_f32 v133, v134, v135
	v_cvt_pk_bf16_f32 v134, v100, v101
	v_cvt_pk_bf16_f32 v135, v102, v103
	v_cvt_pk_bf16_f32 v128, v128, v129
	v_cvt_pk_bf16_f32 v129, v130, v131
	v_cvt_pk_bf16_f32 v130, v96, v97
	v_cvt_pk_bf16_f32 v131, v98, v99
	v_or_b32_e32 v170, s11, v216
	v_mad_i64_i32 v[170:171], vcc, v170, s10, 0
	v_lshlrev_b64 v[170:171], 2, v[170:171]
	v_lshl_add_u64 v[170:171], v[170:171], 0, v[190:191]
	v_lshl_add_u64 v[172:173], s[50:51], 0, v[170:171]
	v_lshl_add_u64 v[170:171], s[92:93], 0, v[170:171]
	s_and_saveexec_b64 s[0:1], s[42:43]
	global_store_dwordx4 v[172:173], v[200:203], off
	global_store_dwordx4 v[172:173], v[204:207], off offset:16
	global_store_dwordx4 v[170:171], v[192:195], off
	global_store_dwordx4 v[170:171], v[240:243], off offset:16
	s_or_b64 exec, exec, s[0:1]
	v_add_u32_e32 v170, s11, v218
	v_mad_i64_i32 v[170:171], vcc, v170, s10, 0
	v_lshlrev_b64 v[170:171], 2, v[170:171]
	v_lshl_add_u64 v[170:171], s[52:53], 0, v[170:171]
	v_lshl_add_u64 v[170:171], v[188:189], 2, v[170:171]
	s_and_saveexec_b64 s[0:1], s[44:45]
	global_store_dwordx4 v[170:171], v[150:153], off
	global_store_dwordx4 v[170:171], v[120:123], off offset:16
	s_or_b64 exec, exec, s[0:1]
	v_mov_b64_e32 v[170:171], s[94:95]
	v_mad_i64_i32 v[170:171], vcc, v198, s20, v[170:171]
	v_lshl_add_u64 v[170:171], v[188:189], 1, v[170:171]
	s_and_saveexec_b64 s[0:1], s[40:41]
	global_store_dwordx4 v[170:171], v[140:143], off
	s_or_b64 exec, exec, s[0:1]
	v_or_b32_e32 v172, 16, v198
	v_mov_b64_e32 v[170:171], s[94:95]
	v_mad_i64_i32 v[170:171], vcc, v172, s20, v[170:171]
	v_lshl_add_u64 v[170:171], v[188:189], 1, v[170:171]
	global_store_dwordx4 v[170:171], v[136:139], off
	v_or_b32_e32 v172, 32, v198
	v_mov_b64_e32 v[170:171], s[94:95]
	v_mad_i64_i32 v[170:171], vcc, v172, s20, v[170:171]
	v_lshl_add_u64 v[170:171], v[188:189], 1, v[170:171]
	global_store_dwordx4 v[170:171], v[132:135], off
	v_or_b32_e32 v172, 48, v198
	v_mov_b64_e32 v[170:171], s[94:95]
	v_mad_i64_i32 v[170:171], vcc, v172, s20, v[170:171]
	v_lshl_add_u64 v[170:171], v[188:189], 1, v[170:171]
	global_store_dwordx4 v[170:171], v[128:131], off
	s_add_i32 s11, s11, 4
	v_mul_f32_e32 v48, v48, v248
	v_mul_f32_e32 v60, v60, v249
	v_mul_f32_e32 v56, v56, v250
	v_mul_f32_e32 v52, v52, v251
	v_mul_f32_e32 v49, v49, v248
	v_mul_f32_e32 v61, v61, v249
	v_mul_f32_e32 v57, v57, v250
	v_mul_f32_e32 v53, v53, v251
	v_cndmask_b32_e64 v221, v48, 0, s[36:37]
	v_cndmask_b32_e64 v225, v48, 0, s[44:45]
	v_cndmask_b32_e64 v222, v60, v48, s[36:37]
	v_cndmask_b32_e64 v226, v60, v48, s[44:45]
	v_cndmask_b32_e64 v223, v56, v60, s[36:37]
	v_cndmask_b32_e64 v227, v56, v60, s[44:45]
	v_cndmask_b32_e64 v224, v52, v56, s[36:37]
	v_cndmask_b32_e64 v228, v52, v56, s[44:45]
	v_cndmask_b32_e64 v232, v49, 0, s[36:37]
	v_cndmask_b32_e64 v236, v49, 0, s[44:45]
	v_cndmask_b32_e64 v233, v61, v49, s[36:37]
	v_cndmask_b32_e64 v237, v61, v49, s[44:45]
	v_cndmask_b32_e64 v234, v57, v61, s[36:37]
	v_cndmask_b32_e64 v238, v57, v61, s[44:45]
	v_cndmask_b32_e64 v235, v53, v57, s[36:37]
	v_cndmask_b32_e64 v239, v53, v57, s[44:45]
	v_fma_f32 v200, v92, v48, v84
	v_fma_f32 v229, v92, v60, v84
	v_fma_f32 v230, v92, v56, v84
	v_fma_f32 v231, v92, v52, v84
	v_fma_f32 v201, v93, v49, v85
	v_fma_f32 v196, v93, v61, v85
	v_fma_f32 v197, v93, v57, v85
	v_fma_f32 v176, v93, v53, v85
	v_fmac_f32_dpp v200, v221, v88 row_ror:1 row_mask:0xf bank_mask:0xf
	v_fmac_f32_dpp v229, v222, v88 row_ror:1 row_mask:0xf bank_mask:0xf
	v_fmac_f32_dpp v230, v223, v88 row_ror:1 row_mask:0xf bank_mask:0xf
	v_fmac_f32_dpp v231, v224, v88 row_ror:1 row_mask:0xf bank_mask:0xf
	v_fmac_f32_dpp v201, v232, v89 row_ror:1 row_mask:0xf bank_mask:0xf
	v_fmac_f32_dpp v196, v233, v89 row_ror:1 row_mask:0xf bank_mask:0xf
	v_fmac_f32_dpp v197, v234, v89 row_ror:1 row_mask:0xf bank_mask:0xf
	v_fmac_f32_dpp v176, v235, v89 row_ror:1 row_mask:0xf bank_mask:0xf
	v_fmac_f32_dpp v200, v225, v80 row_ror:2 row_mask:0xf bank_mask:0xf
	v_fmac_f32_dpp v229, v226, v80 row_ror:2 row_mask:0xf bank_mask:0xf
	v_fmac_f32_dpp v230, v227, v80 row_ror:2 row_mask:0xf bank_mask:0xf
	v_fmac_f32_dpp v231, v228, v80 row_ror:2 row_mask:0xf bank_mask:0xf
	v_fmac_f32_dpp v201, v236, v81 row_ror:2 row_mask:0xf bank_mask:0xf
	v_fmac_f32_dpp v196, v237, v81 row_ror:2 row_mask:0xf bank_mask:0xf
	v_fmac_f32_dpp v197, v238, v81 row_ror:2 row_mask:0xf bank_mask:0xf
	v_fmac_f32_dpp v176, v239, v81 row_ror:2 row_mask:0xf bank_mask:0xf
	v_mul_f32_e32 v221, 0xbfb8aa3b, v200
	v_mul_f32_e32 v222, 0xbfb8aa3b, v229
	v_mul_f32_e32 v223, 0xbfb8aa3b, v230
	v_mul_f32_e32 v224, 0xbfb8aa3b, v231
	v_mul_f32_e32 v232, 0xbfb8aa3b, v201
	v_mul_f32_e32 v233, 0xbfb8aa3b, v196
	v_mul_f32_e32 v234, 0xbfb8aa3b, v197
	v_mul_f32_e32 v235, 0xbfb8aa3b, v176
	v_exp_f32_e32 v221, v221
	v_exp_f32_e32 v222, v222
	v_exp_f32_e32 v223, v223
	v_exp_f32_e32 v224, v224
	v_exp_f32_e32 v232, v232
	v_exp_f32_e32 v233, v233
	v_exp_f32_e32 v234, v234
	v_exp_f32_e32 v235, v235
	v_add_f32_e32 v221, 1.0, v221
	v_add_f32_e32 v222, 1.0, v222
	v_add_f32_e32 v223, 1.0, v223
	v_add_f32_e32 v224, 1.0, v224
	v_add_f32_e32 v232, 1.0, v232
	v_add_f32_e32 v233, 1.0, v233
	v_add_f32_e32 v234, 1.0, v234
	v_add_f32_e32 v235, 1.0, v235
	v_rcp_f32_e32 v221, v221
	v_rcp_f32_e32 v222, v222
	v_rcp_f32_e32 v223, v223
	v_rcp_f32_e32 v224, v224
	v_rcp_f32_e32 v232, v232
	v_rcp_f32_e32 v233, v233
	v_rcp_f32_e32 v234, v234
	v_rcp_f32_e32 v235, v235
	v_mul_f32_e32 v221, v200, v221
	v_mul_f32_e32 v222, v229, v222
	v_mul_f32_e32 v223, v230, v223
	v_mul_f32_e32 v224, v231, v224
	v_mul_f32_e32 v232, v201, v232
	v_mul_f32_e32 v233, v196, v233
	v_mul_f32_e32 v234, v197, v234
	v_mul_f32_e32 v235, v176, v235
	v_mul_f32_e32 v192, v44, v248
	v_mul_f32_e32 v40, v40, v249
	v_mul_f32_e32 v36, v36, v250
	v_mul_f32_e32 v32, v32, v251
	v_mul_f32_e32 v193, v45, v248
	v_mul_f32_e32 v41, v41, v249
	v_mul_f32_e32 v37, v37, v250
	v_mul_f32_e32 v33, v33, v251
	v_mul_f32_e32 v44, v221, v192
	v_mul_f32_e32 v40, v222, v40
	v_mul_f32_e32 v36, v223, v36
	v_mul_f32_e32 v32, v224, v32
	v_mul_f32_e32 v45, v232, v193
	v_mul_f32_e32 v41, v233, v41
	v_mul_f32_e32 v37, v234, v37
	v_mul_f32_e32 v33, v235, v33
	v_mul_f32_e32 v50, v50, v248
	v_mul_f32_e32 v62, v62, v249
	v_mul_f32_e32 v58, v58, v250
	v_mul_f32_e32 v54, v54, v251
	v_mul_f32_e32 v51, v51, v248
	v_mul_f32_e32 v63, v63, v249
	v_mul_f32_e32 v59, v59, v250
	v_mul_f32_e32 v55, v55, v251
	v_cndmask_b32_e64 v221, v50, 0, s[36:37]
	v_cndmask_b32_e64 v225, v50, 0, s[44:45]
	v_cndmask_b32_e64 v222, v62, v50, s[36:37]
	v_cndmask_b32_e64 v226, v62, v50, s[44:45]
	v_cndmask_b32_e64 v223, v58, v62, s[36:37]
	v_cndmask_b32_e64 v227, v58, v62, s[44:45]
	v_cndmask_b32_e64 v224, v54, v58, s[36:37]
	v_cndmask_b32_e64 v228, v54, v58, s[44:45]
	v_cndmask_b32_e64 v232, v51, 0, s[36:37]
	v_cndmask_b32_e64 v236, v51, 0, s[44:45]
	v_cndmask_b32_e64 v233, v63, v51, s[36:37]
	v_cndmask_b32_e64 v237, v63, v51, s[44:45]
	v_cndmask_b32_e64 v234, v59, v63, s[36:37]
	v_cndmask_b32_e64 v238, v59, v63, s[44:45]
	v_cndmask_b32_e64 v235, v55, v59, s[36:37]
	v_cndmask_b32_e64 v239, v55, v59, s[44:45]
	v_fma_f32 v202, v94, v50, v86
	v_fma_f32 v229, v94, v62, v86
	v_fma_f32 v230, v94, v58, v86
	v_fma_f32 v231, v94, v54, v86
	v_fma_f32 v203, v95, v51, v87
	v_fma_f32 v196, v95, v63, v87
	v_fma_f32 v197, v95, v59, v87
	v_fma_f32 v176, v95, v55, v87
	v_fmac_f32_dpp v202, v221, v90 row_ror:1 row_mask:0xf bank_mask:0xf
	v_fmac_f32_dpp v229, v222, v90 row_ror:1 row_mask:0xf bank_mask:0xf
	v_fmac_f32_dpp v230, v223, v90 row_ror:1 row_mask:0xf bank_mask:0xf
	v_fmac_f32_dpp v231, v224, v90 row_ror:1 row_mask:0xf bank_mask:0xf
	v_fmac_f32_dpp v203, v232, v91 row_ror:1 row_mask:0xf bank_mask:0xf
	v_fmac_f32_dpp v196, v233, v91 row_ror:1 row_mask:0xf bank_mask:0xf
	v_fmac_f32_dpp v197, v234, v91 row_ror:1 row_mask:0xf bank_mask:0xf
	v_fmac_f32_dpp v176, v235, v91 row_ror:1 row_mask:0xf bank_mask:0xf
	v_fmac_f32_dpp v202, v225, v82 row_ror:2 row_mask:0xf bank_mask:0xf
	v_fmac_f32_dpp v229, v226, v82 row_ror:2 row_mask:0xf bank_mask:0xf
	v_fmac_f32_dpp v230, v227, v82 row_ror:2 row_mask:0xf bank_mask:0xf
	v_fmac_f32_dpp v231, v228, v82 row_ror:2 row_mask:0xf bank_mask:0xf
	v_fmac_f32_dpp v203, v236, v83 row_ror:2 row_mask:0xf bank_mask:0xf
	v_fmac_f32_dpp v196, v237, v83 row_ror:2 row_mask:0xf bank_mask:0xf
	v_fmac_f32_dpp v197, v238, v83 row_ror:2 row_mask:0xf bank_mask:0xf
	v_fmac_f32_dpp v176, v239, v83 row_ror:2 row_mask:0xf bank_mask:0xf
	v_mul_f32_e32 v221, 0xbfb8aa3b, v202
	v_mul_f32_e32 v222, 0xbfb8aa3b, v229
	v_mul_f32_e32 v223, 0xbfb8aa3b, v230
	v_mul_f32_e32 v224, 0xbfb8aa3b, v231
	v_mul_f32_e32 v232, 0xbfb8aa3b, v203
	v_mul_f32_e32 v233, 0xbfb8aa3b, v196
	v_mul_f32_e32 v234, 0xbfb8aa3b, v197
	v_mul_f32_e32 v235, 0xbfb8aa3b, v176
	v_exp_f32_e32 v221, v221
	v_exp_f32_e32 v222, v222
	v_exp_f32_e32 v223, v223
	v_exp_f32_e32 v224, v224
	v_exp_f32_e32 v232, v232
	v_exp_f32_e32 v233, v233
	v_exp_f32_e32 v234, v234
	v_exp_f32_e32 v235, v235
	v_add_f32_e32 v221, 1.0, v221
	v_add_f32_e32 v222, 1.0, v222
	v_add_f32_e32 v223, 1.0, v223
	v_add_f32_e32 v224, 1.0, v224
	v_add_f32_e32 v232, 1.0, v232
	v_add_f32_e32 v233, 1.0, v233
	v_add_f32_e32 v234, 1.0, v234
	v_add_f32_e32 v235, 1.0, v235
	v_rcp_f32_e32 v221, v221
	v_rcp_f32_e32 v222, v222
	v_rcp_f32_e32 v223, v223
	v_rcp_f32_e32 v224, v224
	v_rcp_f32_e32 v232, v232
	v_rcp_f32_e32 v233, v233
	v_rcp_f32_e32 v234, v234
	v_rcp_f32_e32 v235, v235
	v_mul_f32_e32 v221, v202, v221
	v_mul_f32_e32 v222, v229, v222
	v_mul_f32_e32 v223, v230, v223
	v_mul_f32_e32 v224, v231, v224
	v_mul_f32_e32 v232, v203, v232
	v_mul_f32_e32 v233, v196, v233
	v_mul_f32_e32 v234, v197, v234
	v_mul_f32_e32 v235, v176, v235
	v_mul_f32_e32 v194, v46, v248
	v_mul_f32_e32 v42, v42, v249
	v_mul_f32_e32 v38, v38, v250
	v_mul_f32_e32 v34, v34, v251
	v_mul_f32_e32 v195, v47, v248
	v_mul_f32_e32 v43, v43, v249
	v_mul_f32_e32 v39, v39, v250
	v_mul_f32_e32 v35, v35, v251
	v_mul_f32_e32 v46, v221, v194
	v_mul_f32_e32 v42, v222, v42
	v_mul_f32_e32 v38, v223, v38
	v_mul_f32_e32 v34, v224, v34
	v_mul_f32_e32 v47, v232, v195
	v_mul_f32_e32 v43, v233, v43
	v_mul_f32_e32 v39, v234, v39
	v_mul_f32_e32 v35, v235, v35
	v_mul_f32_e32 v20, v20, v248
	v_mul_f32_e32 v28, v28, v249
	v_mul_f32_e32 v16, v16, v250
	v_mul_f32_e32 v24, v24, v251
	v_mul_f32_e32 v21, v21, v248
	v_mul_f32_e32 v29, v29, v249
	v_mul_f32_e32 v17, v17, v250
	v_mul_f32_e32 v25, v25, v251
	v_cndmask_b32_e64 v221, v20, 0, s[36:37]
	v_cndmask_b32_e64 v225, v20, 0, s[44:45]
	v_cndmask_b32_e64 v222, v28, v20, s[36:37]
	v_cndmask_b32_e64 v226, v28, v20, s[44:45]
	v_cndmask_b32_e64 v223, v16, v28, s[36:37]
	v_cndmask_b32_e64 v227, v16, v28, s[44:45]
	v_cndmask_b32_e64 v224, v24, v16, s[36:37]
	v_cndmask_b32_e64 v228, v24, v16, s[44:45]
	v_cndmask_b32_e64 v232, v21, 0, s[36:37]
	v_cndmask_b32_e64 v236, v21, 0, s[44:45]
	v_cndmask_b32_e64 v233, v29, v21, s[36:37]
	v_cndmask_b32_e64 v237, v29, v21, s[44:45]
	v_cndmask_b32_e64 v234, v17, v29, s[36:37]
	v_cndmask_b32_e64 v238, v17, v29, s[44:45]
	v_cndmask_b32_e64 v235, v25, v17, s[36:37]
	v_cndmask_b32_e64 v239, v25, v17, s[44:45]
	v_fma_f32 v204, v76, v20, v68
	v_fma_f32 v229, v76, v28, v68
	v_fma_f32 v230, v76, v16, v68
	v_fma_f32 v231, v76, v24, v68
	v_fma_f32 v205, v77, v21, v69
	v_fma_f32 v196, v77, v29, v69
	v_fma_f32 v197, v77, v17, v69
	v_fma_f32 v176, v77, v25, v69
	v_fmac_f32_dpp v204, v221, v72 row_ror:1 row_mask:0xf bank_mask:0xf
	v_fmac_f32_dpp v229, v222, v72 row_ror:1 row_mask:0xf bank_mask:0xf
	v_fmac_f32_dpp v230, v223, v72 row_ror:1 row_mask:0xf bank_mask:0xf
	v_fmac_f32_dpp v231, v224, v72 row_ror:1 row_mask:0xf bank_mask:0xf
	v_fmac_f32_dpp v205, v232, v73 row_ror:1 row_mask:0xf bank_mask:0xf
	v_fmac_f32_dpp v196, v233, v73 row_ror:1 row_mask:0xf bank_mask:0xf
	v_fmac_f32_dpp v197, v234, v73 row_ror:1 row_mask:0xf bank_mask:0xf
	v_fmac_f32_dpp v176, v235, v73 row_ror:1 row_mask:0xf bank_mask:0xf
	v_fmac_f32_dpp v204, v225, v64 row_ror:2 row_mask:0xf bank_mask:0xf
	v_fmac_f32_dpp v229, v226, v64 row_ror:2 row_mask:0xf bank_mask:0xf
	v_fmac_f32_dpp v230, v227, v64 row_ror:2 row_mask:0xf bank_mask:0xf
	v_fmac_f32_dpp v231, v228, v64 row_ror:2 row_mask:0xf bank_mask:0xf
	v_fmac_f32_dpp v205, v236, v65 row_ror:2 row_mask:0xf bank_mask:0xf
	v_fmac_f32_dpp v196, v237, v65 row_ror:2 row_mask:0xf bank_mask:0xf
	v_fmac_f32_dpp v197, v238, v65 row_ror:2 row_mask:0xf bank_mask:0xf
	v_fmac_f32_dpp v176, v239, v65 row_ror:2 row_mask:0xf bank_mask:0xf
	v_mul_f32_e32 v221, 0xbfb8aa3b, v204
	v_mul_f32_e32 v222, 0xbfb8aa3b, v229
	v_mul_f32_e32 v223, 0xbfb8aa3b, v230
	v_mul_f32_e32 v224, 0xbfb8aa3b, v231
	v_mul_f32_e32 v232, 0xbfb8aa3b, v205
	v_mul_f32_e32 v233, 0xbfb8aa3b, v196
	v_mul_f32_e32 v234, 0xbfb8aa3b, v197
	v_mul_f32_e32 v235, 0xbfb8aa3b, v176
	v_exp_f32_e32 v221, v221
	v_exp_f32_e32 v222, v222
	v_exp_f32_e32 v223, v223
	v_exp_f32_e32 v224, v224
	v_exp_f32_e32 v232, v232
	v_exp_f32_e32 v233, v233
	v_exp_f32_e32 v234, v234
	v_exp_f32_e32 v235, v235
	v_add_f32_e32 v221, 1.0, v221
	v_add_f32_e32 v222, 1.0, v222
	v_add_f32_e32 v223, 1.0, v223
	v_add_f32_e32 v224, 1.0, v224
	v_add_f32_e32 v232, 1.0, v232
	v_add_f32_e32 v233, 1.0, v233
	v_add_f32_e32 v234, 1.0, v234
	v_add_f32_e32 v235, 1.0, v235
	v_rcp_f32_e32 v221, v221
	v_rcp_f32_e32 v222, v222
	v_rcp_f32_e32 v223, v223
	v_rcp_f32_e32 v224, v224
	v_rcp_f32_e32 v232, v232
	v_rcp_f32_e32 v233, v233
	v_rcp_f32_e32 v234, v234
	v_rcp_f32_e32 v235, v235
	v_mul_f32_e32 v221, v204, v221
	v_mul_f32_e32 v222, v229, v222
	v_mul_f32_e32 v223, v230, v223
	v_mul_f32_e32 v224, v231, v224
	v_mul_f32_e32 v232, v205, v232
	v_mul_f32_e32 v233, v196, v233
	v_mul_f32_e32 v234, v197, v234
	v_mul_f32_e32 v235, v176, v235
	v_mul_f32_e32 v240, v12, v248
	v_mul_f32_e32 v8, v8, v249
	v_mul_f32_e32 v4, v4, v250
	v_mul_f32_e32 v0, v0, v251
	v_mul_f32_e32 v241, v13, v248
	v_mul_f32_e32 v9, v9, v249
	v_mul_f32_e32 v5, v5, v250
	v_mul_f32_e32 v1, v1, v251
	v_mul_f32_e32 v12, v221, v240
	v_mul_f32_e32 v8, v222, v8
	v_mul_f32_e32 v4, v223, v4
	v_mul_f32_e32 v0, v224, v0
	v_mul_f32_e32 v13, v232, v241
	v_mul_f32_e32 v9, v233, v9
	v_mul_f32_e32 v5, v234, v5
	v_mul_f32_e32 v1, v235, v1
	v_mul_f32_e32 v22, v22, v248
	v_mul_f32_e32 v30, v30, v249
	v_mul_f32_e32 v18, v18, v250
	v_mul_f32_e32 v26, v26, v251
	v_mul_f32_e32 v23, v23, v248
	v_mul_f32_e32 v31, v31, v249
	v_mul_f32_e32 v19, v19, v250
	v_mul_f32_e32 v27, v27, v251
	v_cndmask_b32_e64 v221, v22, 0, s[36:37]
	v_cndmask_b32_e64 v225, v22, 0, s[44:45]
	v_cndmask_b32_e64 v222, v30, v22, s[36:37]
	v_cndmask_b32_e64 v226, v30, v22, s[44:45]
	v_cndmask_b32_e64 v223, v18, v30, s[36:37]
	v_cndmask_b32_e64 v227, v18, v30, s[44:45]
	v_cndmask_b32_e64 v224, v26, v18, s[36:37]
	v_cndmask_b32_e64 v228, v26, v18, s[44:45]
	v_cndmask_b32_e64 v232, v23, 0, s[36:37]
	v_cndmask_b32_e64 v236, v23, 0, s[44:45]
	v_cndmask_b32_e64 v233, v31, v23, s[36:37]
	v_cndmask_b32_e64 v237, v31, v23, s[44:45]
	v_cndmask_b32_e64 v234, v19, v31, s[36:37]
	v_cndmask_b32_e64 v238, v19, v31, s[44:45]
	v_cndmask_b32_e64 v235, v27, v19, s[36:37]
	v_cndmask_b32_e64 v239, v27, v19, s[44:45]
	v_fma_f32 v206, v78, v22, v70
	v_fma_f32 v229, v78, v30, v70
	v_fma_f32 v230, v78, v18, v70
	v_fma_f32 v231, v78, v26, v70
	v_fma_f32 v207, v79, v23, v71
	v_fma_f32 v196, v79, v31, v71
	v_fma_f32 v197, v79, v19, v71
	v_fma_f32 v176, v79, v27, v71
	v_fmac_f32_dpp v206, v221, v74 row_ror:1 row_mask:0xf bank_mask:0xf
	v_fmac_f32_dpp v229, v222, v74 row_ror:1 row_mask:0xf bank_mask:0xf
	v_fmac_f32_dpp v230, v223, v74 row_ror:1 row_mask:0xf bank_mask:0xf
	v_fmac_f32_dpp v231, v224, v74 row_ror:1 row_mask:0xf bank_mask:0xf
	v_fmac_f32_dpp v207, v232, v75 row_ror:1 row_mask:0xf bank_mask:0xf
	v_fmac_f32_dpp v196, v233, v75 row_ror:1 row_mask:0xf bank_mask:0xf
	v_fmac_f32_dpp v197, v234, v75 row_ror:1 row_mask:0xf bank_mask:0xf
	v_fmac_f32_dpp v176, v235, v75 row_ror:1 row_mask:0xf bank_mask:0xf
	v_fmac_f32_dpp v206, v225, v66 row_ror:2 row_mask:0xf bank_mask:0xf
	v_fmac_f32_dpp v229, v226, v66 row_ror:2 row_mask:0xf bank_mask:0xf
	v_fmac_f32_dpp v230, v227, v66 row_ror:2 row_mask:0xf bank_mask:0xf
	v_fmac_f32_dpp v231, v228, v66 row_ror:2 row_mask:0xf bank_mask:0xf
	v_fmac_f32_dpp v207, v236, v67 row_ror:2 row_mask:0xf bank_mask:0xf
	v_fmac_f32_dpp v196, v237, v67 row_ror:2 row_mask:0xf bank_mask:0xf
	v_fmac_f32_dpp v197, v238, v67 row_ror:2 row_mask:0xf bank_mask:0xf
	v_fmac_f32_dpp v176, v239, v67 row_ror:2 row_mask:0xf bank_mask:0xf
	v_mul_f32_e32 v221, 0xbfb8aa3b, v206
	v_mul_f32_e32 v222, 0xbfb8aa3b, v229
	v_mul_f32_e32 v223, 0xbfb8aa3b, v230
	v_mul_f32_e32 v224, 0xbfb8aa3b, v231
	v_mul_f32_e32 v232, 0xbfb8aa3b, v207
	v_mul_f32_e32 v233, 0xbfb8aa3b, v196
	v_mul_f32_e32 v234, 0xbfb8aa3b, v197
	v_mul_f32_e32 v235, 0xbfb8aa3b, v176
	v_exp_f32_e32 v221, v221
	v_exp_f32_e32 v222, v222
	v_exp_f32_e32 v223, v223
	v_exp_f32_e32 v224, v224
	v_exp_f32_e32 v232, v232
	v_exp_f32_e32 v233, v233
	v_exp_f32_e32 v234, v234
	v_exp_f32_e32 v235, v235
	v_add_f32_e32 v221, 1.0, v221
	v_add_f32_e32 v222, 1.0, v222
	v_add_f32_e32 v223, 1.0, v223
	v_add_f32_e32 v224, 1.0, v224
	v_add_f32_e32 v232, 1.0, v232
	v_add_f32_e32 v233, 1.0, v233
	v_add_f32_e32 v234, 1.0, v234
	v_add_f32_e32 v235, 1.0, v235
	v_rcp_f32_e32 v221, v221
	v_rcp_f32_e32 v222, v222
	v_rcp_f32_e32 v223, v223
	v_rcp_f32_e32 v224, v224
	v_rcp_f32_e32 v232, v232
	v_rcp_f32_e32 v233, v233
	v_rcp_f32_e32 v234, v234
	v_rcp_f32_e32 v235, v235
	v_mul_f32_e32 v221, v206, v221
	v_mul_f32_e32 v222, v229, v222
	v_mul_f32_e32 v223, v230, v223
	v_mul_f32_e32 v224, v231, v224
	v_mul_f32_e32 v232, v207, v232
	v_mul_f32_e32 v233, v196, v233
	v_mul_f32_e32 v234, v197, v234
	v_mul_f32_e32 v235, v176, v235
	v_mul_f32_e32 v242, v14, v248
	v_mul_f32_e32 v10, v10, v249
	v_mul_f32_e32 v6, v6, v250
	v_mul_f32_e32 v2, v2, v251
	v_mul_f32_e32 v243, v15, v248
	v_mul_f32_e32 v11, v11, v249
	v_mul_f32_e32 v7, v7, v250
	v_mul_f32_e32 v3, v3, v251
	v_mul_f32_e32 v14, v221, v242
	v_mul_f32_e32 v10, v222, v10
	v_mul_f32_e32 v6, v223, v6
	v_mul_f32_e32 v2, v224, v2
	v_mul_f32_e32 v15, v232, v243
	v_mul_f32_e32 v11, v233, v11
	v_mul_f32_e32 v7, v234, v7
	v_mul_f32_e32 v3, v235, v3
	v_cvt_pk_bf16_f32 v44, v44, v45
	v_cvt_pk_bf16_f32 v45, v46, v47
	v_cvt_pk_bf16_f32 v46, v12, v13
	v_cvt_pk_bf16_f32 v47, v14, v15
	v_cvt_pk_bf16_f32 v40, v40, v41
	v_cvt_pk_bf16_f32 v41, v42, v43
	v_cvt_pk_bf16_f32 v42, v8, v9
	v_cvt_pk_bf16_f32 v43, v10, v11
	v_cvt_pk_bf16_f32 v36, v36, v37
	v_cvt_pk_bf16_f32 v37, v38, v39
	v_cvt_pk_bf16_f32 v38, v4, v5
	v_cvt_pk_bf16_f32 v39, v6, v7
	v_cvt_pk_bf16_f32 v32, v32, v33
	v_cvt_pk_bf16_f32 v33, v34, v35
	v_cvt_pk_bf16_f32 v34, v0, v1
	v_cvt_pk_bf16_f32 v35, v2, v3
	v_or_b32_e32 v170, s11, v216
	v_mad_i64_i32 v[170:171], vcc, v170, s10, 0
	v_lshlrev_b64 v[170:171], 2, v[170:171]
	v_lshl_add_u64 v[170:171], v[170:171], 0, v[190:191]
	v_lshl_add_u64 v[172:173], s[50:51], 0, v[170:171]
	v_lshl_add_u64 v[170:171], s[92:93], 0, v[170:171]
	s_and_saveexec_b64 s[0:1], s[42:43]
	global_store_dwordx4 v[172:173], v[200:203], off
	global_store_dwordx4 v[172:173], v[204:207], off offset:16
	global_store_dwordx4 v[170:171], v[192:195], off
	global_store_dwordx4 v[170:171], v[240:243], off offset:16
	s_or_b64 exec, exec, s[0:1]
	v_add_u32_e32 v170, s11, v218
	v_mad_i64_i32 v[170:171], vcc, v170, s10, 0
	v_lshlrev_b64 v[170:171], 2, v[170:171]
	v_lshl_add_u64 v[170:171], s[52:53], 0, v[170:171]
	v_lshl_add_u64 v[170:171], v[188:189], 2, v[170:171]
	s_and_saveexec_b64 s[0:1], s[44:45]
	global_store_dwordx4 v[170:171], v[52:55], off
	global_store_dwordx4 v[170:171], v[24:27], off offset:16
	s_or_b64 exec, exec, s[0:1]
	v_mov_b64_e32 v[170:171], s[94:95]
	v_mad_i64_i32 v[170:171], vcc, v168, s20, v[170:171]
	v_lshl_add_u64 v[170:171], v[188:189], 1, v[170:171]
	s_and_saveexec_b64 s[0:1], s[40:41]
	global_store_dwordx4 v[170:171], v[44:47], off
	s_or_b64 exec, exec, s[0:1]
	v_or_b32_e32 v172, 16, v168
	v_mov_b64_e32 v[170:171], s[94:95]
	v_mad_i64_i32 v[170:171], vcc, v172, s20, v[170:171]
	v_lshl_add_u64 v[170:171], v[188:189], 1, v[170:171]
	global_store_dwordx4 v[170:171], v[40:43], off
	v_or_b32_e32 v172, 32, v168
	v_mov_b64_e32 v[170:171], s[94:95]
	v_mad_i64_i32 v[170:171], vcc, v172, s20, v[170:171]
	v_lshl_add_u64 v[170:171], v[188:189], 1, v[170:171]
	global_store_dwordx4 v[170:171], v[36:39], off
	v_or_b32_e32 v172, 48, v168
	v_mov_b64_e32 v[170:171], s[94:95]
	v_mad_i64_i32 v[170:171], vcc, v172, s20, v[170:171]
	v_lshl_add_u64 v[170:171], v[188:189], 1, v[170:171]
	global_store_dwordx4 v[170:171], v[32:35], off
	s_and_b64 vcc, exec, s[46:47]
	s_mov_b32 s0, s76
	s_mov_b32 s84, s78
	s_mov_b64 s[82:83], s[72:73]
	s_mov_b64 s[86:87], s[80:81]
	s_cbranch_vccnz .LBB0_146
	s_branch .LBB0_122
